# attention key loop: next-tile V ds_write (and its vmcnt wait) moved from iteration end to after the second QK block
# speedup vs baseline: 1.0047x; 1.0047x over previous
; #define SB_ __builtin_amdgcn_sched_barrier(0)
; DI void attn_item64(const Params& p, int it, char* smem) {
;     ...
;   for (int kt = 0; kt < NKT; ++kt) {
;     const char* cur = smem + (kt & 1) * STAGE;
;     const bool more = kt + 1 < NKT;
;     if (more) {
;       const bf16_t* kn = Kb + (size_t)(kt + 1) * 64 * QKD; const bf16_t* vn = Vb + (kt + 1) * 64;
;       char* nx = smem + ((kt + 1) & 1) * STAGE;
;       GLDS(kn + kgo0, nx + klo0); if (k1v) GLDS(kn + kgo1, nx + klo1);
;       rv0 = *(const uint4*)(vn + vgo0);
;     }
;     SB_;
; #pragma unroll
;     for (int t2 = 0; t2 < 2; ++t2) {
;       const char* kpe = cur + (t2 * 32 + r) * KROW + swo;
;       const char* kpo = kpe - 2 * sb32;
;       f32x16 sa, sb;
;       { const bf16x8 kf = *(const bf16x8*)(kpe); sa = MFMA(kf, qfa[0], sinit); sb = MFMA(kf, qfb[0], sinit); }
; #pragma unroll
;       for (int c = 1; c < 6; ++c) { const bf16x8 kf = *(const bf16x8*)(((c & 1) ? kpo : kpe) + c * 32); sa = MFMA(kf, qfa[c], sa); sb = MFMA(kf, qfb[c], sb); }
;       SB_;
;       float lsa = 0.f, lsb = 0.f;
; #pragma unroll
;       for (int i = 0; i < 16; ++i) { const float e = __builtin_amdgcn_exp2f(sa[i]); sa[i] = e; lsa += e; const float f = __builtin_amdgcn_exp2f(sb[i]); sb[i] = f; lsb += f; }
;       la += lsa; lb += lsb;
;       SB_;
; #pragma unroll
;       for (int s2 = 0; s2 < 2; ++s2) {
;         uint4 pu, pv;
;         pu.x = pk_bf16(sa[8 * s2 + 0], sa[8 * s2 + 1]); pu.y = pk_bf16(sa[8 * s2 + 2], sa[8 * s2 + 3]); pu.z = pk_bf16(sa[8 * s2 + 4], sa[8 * s2 + 5]); pu.w = pk_bf16(sa[8 * s2 + 6], sa[8 * s2 + 7]);
;         pv.x = pk_bf16(sb[8 * s2 + 0], sb[8 * s2 + 1]); pv.y = pk_bf16(sb[8 * s2 + 2], sb[8 * s2 + 3]); pv.z = pk_bf16(sb[8 * s2 + 4], sb[8 * s2 + 5]); pv.w = pk_bf16(sb[8 * s2 + 6], sb[8 * s2 + 7]);
;         const bf16x8 pa_ = __builtin_bit_cast(bf16x8, pu), pb_ = __builtin_bit_cast(bf16x8, pv);
; #pragma unroll
;         for (int vt = 0; vt < 2; ++vt) {
;           const char* vp = cur + KBYTES + (vt * 32 + r) * VROW + (t2 * 32 + 16 * s2 + 4 * hh) * 2;
;           const uint2 lo = *(const uint2*)(vp), hi = *(const uint2*)(vp + 16);
;           uint4 vu; vu.x = lo.x; vu.y = lo.y; vu.z = hi.x; vu.w = hi.y;
;           const bf16x8 vf = __builtin_bit_cast(bf16x8, vu);
;           oa[vt] = MFMA(vf, pa_, oa[vt]);
;           ob[vt] = MFMA(vf, pb_, ob[vt]);
;         }
;       }
.LBB0_548:
	s_or_b64 exec, exec, s[4:5]
	global_load_dwordx4 v[160:163], v[170:171], off
	s_cmp_eq_u32 s7, 1
	s_cselect_b32 s4, 0, 0x5200
	v_or_b32_e32 v80, s4, v211
	v_add_u32_e32 v80, v80, v210
	v_or_b32_e32 v81, s4, v164
	v_add_u32_e32 v168, v80, v212
	v_add3_u32 v213, v80, v207, v206
	v_add_u32_e32 v80, s6, v209
	v_add_u32_e32 v188, v168, v206
	v_add_u32_e32 v195, v81, v208
	v_add_u32_e32 v238, 0x3000, v80
	ds_read_b128 v[176:179], v168
	ds_read_b128 v[242:245], v188 offset:32
	ds_read_b128 v[180:183], v168 offset:64
	ds_read_b128 v[246:249], v188 offset:96
	ds_read_b128 v[184:187], v168 offset:128
	s_waitcnt lgkmcnt(4)
	v_mfma_f32_32x32x16_bf16 v[80:95], v[176:179], v[152:155], v[64:79]
	v_mfma_f32_32x32x16_bf16 v[96:111], v[176:179], v[156:159], v[64:79]
	ds_read_b128 v[176:179], v188 offset:160
	s_waitcnt lgkmcnt(4)
	v_mfma_f32_32x32x16_bf16 v[80:95], v[242:245], v[136:139], v[80:95]
	v_mfma_f32_32x32x16_bf16 v[96:111], v[242:245], v[140:143], v[96:111]
	s_waitcnt lgkmcnt(3)
	v_mfma_f32_32x32x16_bf16 v[80:95], v[180:183], v[144:147], v[80:95]
	v_mfma_f32_32x32x16_bf16 v[96:111], v[180:183], v[148:151], v[96:111]
	s_waitcnt lgkmcnt(2)
	v_mfma_f32_32x32x16_bf16 v[80:95], v[246:249], v[112:115], v[80:95]
	v_mfma_f32_32x32x16_bf16 v[96:111], v[246:249], v[124:127], v[96:111]
	s_waitcnt lgkmcnt(1)
	v_mfma_f32_32x32x16_bf16 v[80:95], v[184:187], v[128:131], v[80:95]
	v_mfma_f32_32x32x16_bf16 v[96:111], v[184:187], v[132:135], v[96:111]
	s_waitcnt lgkmcnt(0)
	v_mfma_f32_32x32x16_bf16 v[80:95], v[176:179], v[116:119], v[80:95]
	v_mfma_f32_32x32x16_bf16 v[96:111], v[176:179], v[120:123], v[96:111]
	v_add_u32_e32 v239, 0x3000, v195
	v_add_u32_e32 v240, 0x4000, v195
	ds_read2_b64 v[242:245], v239 offset1:2
	ds_read2_b64 v[246:249], v240 offset0:32 offset1:34
	s_nop 10
	v_exp_f32_e32 v214, v80
	v_exp_f32_e32 v215, v81
	v_exp_f32_e32 v216, v82
	v_exp_f32_e32 v217, v83
	v_add_f32_e32 v80, 0, v214
	v_exp_f32_e32 v218, v84
	v_add_f32_e32 v80, v215, v80
	v_exp_f32_e32 v219, v85
	v_add_f32_e32 v80, v216, v80
	v_exp_f32_e32 v222, v86
	v_add_f32_e32 v80, v217, v80
	v_add_f32_e32 v80, v218, v80
	v_add_f32_e32 v80, v219, v80
	v_exp_f32_e32 v96, v96
	v_exp_f32_e32 v97, v97
	v_exp_f32_e32 v98, v98
	v_exp_f32_e32 v99, v99
	v_exp_f32_e32 v100, v100
	v_exp_f32_e32 v101, v101
	v_exp_f32_e32 v102, v102
	v_exp_f32_e32 v188, v87
	v_exp_f32_e32 v189, v103
	v_exp_f32_e32 v186, v88
	v_exp_f32_e32 v187, v104
	v_exp_f32_e32 v190, v89
	v_exp_f32_e32 v191, v105
	v_exp_f32_e32 v192, v90
	v_exp_f32_e32 v193, v106
	v_exp_f32_e32 v180, v91
	v_exp_f32_e32 v181, v107
	v_exp_f32_e32 v182, v92
	v_exp_f32_e32 v183, v108
	v_exp_f32_e32 v184, v93
	v_exp_f32_e32 v185, v109
	v_exp_f32_e32 v176, v94
	v_exp_f32_e32 v177, v110
	v_exp_f32_e32 v178, v95
	v_exp_f32_e32 v179, v111
	v_add_f32_e32 v194, v222, v80
	v_cvt_pk_bf16_f32 v84, v214, v215
	v_cvt_pk_bf16_f32 v85, v216, v217
	v_cvt_pk_bf16_f32 v86, v218, v219
	v_cvt_pk_bf16_f32 v87, v222, v188
	v_cvt_pk_bf16_f32 v88, v96, v97
	v_cvt_pk_bf16_f32 v89, v98, v99
	v_cvt_pk_bf16_f32 v90, v100, v101
	v_cvt_pk_bf16_f32 v91, v102, v189
	s_waitcnt lgkmcnt(0)
	v_mfma_f32_32x32x16_bf16 v[48:63], v[242:245], v[84:87], v[48:63]
	v_mfma_f32_32x32x16_bf16 v[32:47], v[242:245], v[88:91], v[32:47]
	ds_read2_b64 v[214:217], v239 offset0:4 offset1:6
	ds_read2_b64 v[222:225], v240 offset0:36 offset1:38
	s_waitcnt lgkmcnt(2)
	v_mfma_f32_32x32x16_bf16 v[16:31], v[246:249], v[84:87], v[16:31]
	v_add_f32_e32 v84, 0, v96
	v_add_f32_e32 v84, v97, v84
	v_add_f32_e32 v84, v98, v84
	v_add_f32_e32 v84, v99, v84
	v_add_f32_e32 v84, v100, v84
	v_add_f32_e32 v84, v101, v84
	v_add_f32_e32 v195, v102, v84
	v_mfma_f32_32x32x16_bf16 v[0:15], v[246:249], v[88:91], v[0:15]
	ds_read_b128 v[226:229], v168 offset:6144
	ds_read_b128 v[242:245], v213 offset:32
	ds_read_b128 v[230:233], v168 offset:6208
	ds_read_b128 v[246:249], v213 offset:96
	ds_read_b128 v[234:237], v168 offset:6272
	s_waitcnt lgkmcnt(4)
	v_mfma_f32_32x32x16_bf16 v[80:95], v[226:229], v[152:155], v[64:79]
	v_mfma_f32_32x32x16_bf16 v[96:111], v[226:229], v[156:159], v[64:79]
	ds_read_b128 v[226:229], v213 offset:160
	s_waitcnt lgkmcnt(4)
	v_mfma_f32_32x32x16_bf16 v[80:95], v[242:245], v[136:139], v[80:95]
	v_mfma_f32_32x32x16_bf16 v[96:111], v[242:245], v[140:143], v[96:111]
	s_waitcnt lgkmcnt(3)
	v_mfma_f32_32x32x16_bf16 v[80:95], v[230:233], v[144:147], v[80:95]
	v_mfma_f32_32x32x16_bf16 v[96:111], v[230:233], v[148:151], v[96:111]
	s_waitcnt lgkmcnt(2)
	v_mfma_f32_32x32x16_bf16 v[80:95], v[246:249], v[112:115], v[80:95]
	v_mfma_f32_32x32x16_bf16 v[96:111], v[246:249], v[124:127], v[96:111]
	s_waitcnt lgkmcnt(1)
	v_mfma_f32_32x32x16_bf16 v[80:95], v[234:237], v[128:131], v[80:95]
	v_mfma_f32_32x32x16_bf16 v[96:111], v[234:237], v[132:135], v[96:111]
	s_waitcnt lgkmcnt(0)
; #define MFMA(a, b, c) __builtin_amdgcn_mfma_f32_32x32x16_bf16((a), (b), (c), 0, 0, 0)
; DI unsigned pk_bf16(float lo, float hi) { f32x2v v = {lo, hi}; bf16x2v b = __builtin_convertvector(v, bf16x2v); return __builtin_bit_cast(unsigned, b); }
; #define SB_ __builtin_amdgcn_sched_barrier(0)
; #define ATT64_STORE(base) do { \
;     { uint2* d = (uint2*)((base) + vlo0); d[0] = make_uint2(rv0.x, rv0.y); d[1] = make_uint2(rv0.z, rv0.w); } } while (0)
; DI void attn_item64(const Params& p, int it, char* smem) {
;     ...
;       { const bf16x8 kf = *(const bf16x8*)(kpe); sa = MFMA(kf, qfa[0], sinit); sb = MFMA(kf, qfb[0], sinit); }
; #pragma unroll
;       for (int c = 1; c < 6; ++c) { const bf16x8 kf = *(const bf16x8*)(((c & 1) ? kpo : kpe) + c * 32); sa = MFMA(kf, qfa[c], sa); sb = MFMA(kf, qfb[c], sb); }
;       SB_;
;       float lsa = 0.f, lsb = 0.f;
; #pragma unroll
;       for (int i = 0; i < 16; ++i) { const float e = __builtin_amdgcn_exp2f(sa[i]); sa[i] = e; lsa += e; const float f = __builtin_amdgcn_exp2f(sb[i]); sb[i] = f; lsb += f; }
;       la += lsa; lb += lsb;
;       SB_;
; #pragma unroll
;       for (int s2 = 0; s2 < 2; ++s2) {
;         uint4 pu, pv;
;         pu.x = pk_bf16(sa[8 * s2 + 0], sa[8 * s2 + 1]); pu.y = pk_bf16(sa[8 * s2 + 2], sa[8 * s2 + 3]); pu.z = pk_bf16(sa[8 * s2 + 4], sa[8 * s2 + 5]); pu.w = pk_bf16(sa[8 * s2 + 6], sa[8 * s2 + 7]);
;         pv.x = pk_bf16(sb[8 * s2 + 0], sb[8 * s2 + 1]); pv.y = pk_bf16(sb[8 * s2 + 2], sb[8 * s2 + 3]); pv.z = pk_bf16(sb[8 * s2 + 4], sb[8 * s2 + 5]); pv.w = pk_bf16(sb[8 * s2 + 6], sb[8 * s2 + 7]);
;         const bf16x8 pa_ = __builtin_bit_cast(bf16x8, pu), pb_ = __builtin_bit_cast(bf16x8, pv);
; #pragma unroll
;         for (int vt = 0; vt < 2; ++vt) {
;           const char* vp = cur + KBYTES + (vt * 32 + r) * VROW + (t2 * 32 + 16 * s2 + 4 * hh) * 2;
;           const uint2 lo = *(const uint2*)(vp), hi = *(const uint2*)(vp + 16);
;           uint4 vu; vu.x = lo.x; vu.y = lo.y; vu.z = hi.x; vu.w = hi.y;
;           const bf16x8 vf = __builtin_bit_cast(bf16x8, vu);
;           oa[vt] = MFMA(vf, pa_, oa[vt]);
;           ob[vt] = MFMA(vf, pb_, ob[vt]);
;         }
;       }
;       SB_;
;     }
;     SB_;
;     if (more) { char* nxt = smem + ((kt + 1) & 1) * STAGE; ATT64_STORE(nxt); }
;     __syncthreads();
	v_mfma_f32_32x32x16_bf16 v[80:95], v[226:229], v[116:119], v[80:95]
	v_mfma_f32_32x32x16_bf16 v[96:111], v[226:229], v[120:123], v[96:111]
	s_waitcnt vmcnt(0)
	ds_write2_b64 v238, v[160:161], v[162:163] offset1:1
	s_nop 10
	v_exp_f32_e32 v168, v80
	v_exp_f32_e32 v213, v81
	v_exp_f32_e32 v233, v96
	v_exp_f32_e32 v96, v82
	v_exp_f32_e32 v234, v97
	v_exp_f32_e32 v97, v83
	v_add_f32_e32 v80, 0, v168
	v_exp_f32_e32 v235, v98
	v_exp_f32_e32 v98, v84
	v_add_f32_e32 v80, v213, v80
	v_exp_f32_e32 v236, v99
	v_exp_f32_e32 v99, v85
	v_add_f32_e32 v80, v96, v80
	v_add_f32_e32 v80, v97, v80
	v_add_f32_e32 v80, v98, v80
	v_exp_f32_e32 v237, v100
	v_exp_f32_e32 v241, v101
	v_exp_f32_e32 v100, v86
	v_exp_f32_e32 v101, v102
	v_exp_f32_e32 v102, v87
	v_exp_f32_e32 v103, v103
	v_exp_f32_e32 v218, v88
	v_exp_f32_e32 v219, v104
	v_exp_f32_e32 v104, v89
	v_exp_f32_e32 v105, v105
	v_exp_f32_e32 v226, v90
	v_exp_f32_e32 v227, v106
	v_exp_f32_e32 v106, v91
	v_exp_f32_e32 v107, v107
	v_exp_f32_e32 v228, v92
	v_exp_f32_e32 v229, v108
	v_exp_f32_e32 v108, v93
	v_exp_f32_e32 v109, v109
	v_exp_f32_e32 v230, v94
	v_exp_f32_e32 v231, v110
	v_exp_f32_e32 v110, v95
	v_exp_f32_e32 v111, v111
	v_add_f32_e32 v232, v99, v80
	v_cvt_pk_bf16_f32 v80, v186, v190
	v_cvt_pk_bf16_f32 v81, v192, v180
	v_cvt_pk_bf16_f32 v82, v182, v184
	v_cvt_pk_bf16_f32 v83, v176, v178
	v_cvt_pk_bf16_f32 v84, v187, v191
	v_cvt_pk_bf16_f32 v85, v193, v181
	v_mfma_f32_32x32x16_bf16 v[48:63], v[214:217], v[80:83], v[48:63]
	v_cvt_pk_bf16_f32 v86, v183, v185
	v_cvt_pk_bf16_f32 v87, v177, v179
	v_cvt_pk_bf16_f32 v88, v233, v234
	v_cvt_pk_bf16_f32 v89, v235, v236
	v_cvt_pk_bf16_f32 v90, v237, v241
	v_cvt_pk_bf16_f32 v91, v101, v103
	v_mfma_f32_32x32x16_bf16 v[16:31], v[222:225], v[80:83], v[16:31]
	ds_read2_b64 v[80:83], v239 offset0:8 offset1:10
	ds_read2_b64 v[246:249], v240 offset0:40 offset1:42
	v_mfma_f32_32x32x16_bf16 v[32:47], v[214:217], v[84:87], v[32:47]
	v_mfma_f32_32x32x16_bf16 v[0:15], v[222:225], v[84:87], v[0:15]
	v_cvt_pk_bf16_f32 v84, v168, v213
	v_cvt_pk_bf16_f32 v85, v96, v97
	v_cvt_pk_bf16_f32 v86, v98, v99
	v_cvt_pk_bf16_f32 v87, v100, v102
	s_waitcnt lgkmcnt(0)
	s_nop 0
	v_mfma_f32_32x32x16_bf16 v[48:63], v[80:83], v[84:87], v[48:63]
	v_mfma_f32_32x32x16_bf16 v[32:47], v[80:83], v[88:91], v[32:47]
	ds_read2_b64 v[92:95], v239 offset0:12 offset1:14
	ds_read2_b64 v[96:99], v240 offset0:44 offset1:46
	s_waitcnt lgkmcnt(2)
	v_mfma_f32_32x32x16_bf16 v[16:31], v[246:249], v[84:87], v[16:31]
	v_add_f32_e32 v84, 0, v233
	v_add_f32_e32 v84, v234, v84
	v_add_f32_e32 v84, v235, v84
	v_add_f32_e32 v84, v236, v84
	v_add_f32_e32 v84, v237, v84
	v_add_f32_e32 v233, v241, v84
	v_pk_add_f32 v[84:85], v[188:189], v[194:195]
	v_mfma_f32_32x32x16_bf16 v[0:15], v[246:249], v[88:91], v[0:15]
	v_add_f32_e64 v80, v186, v84
	v_add_f32_e64 v81, v187, v85
	v_add_f32_e64 v90, v100, v232
	v_add_f32_e64 v91, v101, v233
	v_add_f32_e64 v80, v190, v80
	v_add_f32_e64 v81, v191, v81
	v_pk_add_f32 v[90:91], v[102:103], v[90:91]
	v_pk_add_f32 v[84:85], v[192:193], v[80:81]
	v_cvt_pk_bf16_f32 v80, v218, v104
	v_pk_add_f32 v[84:85], v[180:181], v[84:85]
	v_cvt_pk_bf16_f32 v81, v226, v106
	v_pk_add_f32 v[84:85], v[182:183], v[84:85]
	v_cvt_pk_bf16_f32 v82, v228, v108
	v_cvt_pk_bf16_f32 v83, v230, v110
	v_pk_add_f32 v[88:89], v[184:185], v[84:85]
	v_cvt_pk_bf16_f32 v84, v219, v105
	v_cvt_pk_bf16_f32 v85, v227, v107
	v_cvt_pk_bf16_f32 v86, v229, v109
	v_cvt_pk_bf16_f32 v87, v231, v111
	v_pk_add_f32 v[90:91], v[218:219], v[90:91]
	s_waitcnt lgkmcnt(1)
	v_mfma_f32_32x32x16_bf16 v[48:63], v[92:95], v[80:83], v[48:63]
	v_add_f32_e64 v90, v104, v90
	v_add_f32_e64 v91, v105, v91
	v_add_f32_e64 v88, v176, v88
	v_add_f32_e64 v89, v177, v89
	v_add_f32_e64 v88, v178, v88
	v_add_f32_e64 v89, v179, v89
	v_pk_add_f32 v[88:89], v[166:167], v[88:89]
	v_mfma_f32_32x32x16_bf16 v[32:47], v[92:95], v[84:87], v[32:47]
	s_waitcnt lgkmcnt(0)
	v_mfma_f32_32x32x16_bf16 v[16:31], v[96:99], v[80:83], v[16:31]
	v_add_f32_e64 v80, v226, v90
	v_add_f32_e64 v81, v227, v91
	v_add_f32_e64 v80, v106, v80
	v_add_f32_e64 v81, v107, v81
	v_add_f32_e64 v80, v228, v80
	v_add_f32_e64 v81, v229, v81
	v_pk_add_f32 v[80:81], v[108:109], v[80:81]
	v_mfma_f32_32x32x16_bf16 v[0:15], v[96:99], v[84:87], v[0:15]
	v_add_f32_e64 v80, v230, v80
	v_add_f32_e64 v81, v231, v81
	v_add_f32_e64 v80, v110, v80
	v_add_f32_e64 v81, v111, v81
	v_add_f32_e64 v166, v88, v80
	v_add_f32_e64 v167, v89, v81
	s_add_i32 s8, s8, 1
	v_lshl_add_u64 v[170:171], v[170:171], 0, s[30:31]
	v_lshl_add_u64 v[172:173], v[172:173], 0, s[34:35]
	s_cmp_lg_u32 s8, 36
	v_lshl_add_u64 v[174:175], v[174:175], 0, s[34:35]
	s_waitcnt lgkmcnt(0)
	s_barrier
	s_cbranch_scc0 .LBB0_551
